# v25 + in-projection K-loop MFMAs reordered operand-stationary inside each 8-MFMA k-step group (A fragment fixed for 4 consecutive MFMAs; bit-identical results)
# baseline (speedup 1.0000x reference)
; #define PG8_STAGE(bufoff, gbase, voff) do { _Pragma("unroll") for (int _i = 0; _i < 2; ++_i) \
;         __builtin_amdgcn_global_load_lds((const unsigned*)((const char*)(gbase) + (voff)[_i]), (PG8_LAS unsigned*)(lds + (bufoff) + ldsw + _i * 8192), 16, 0, 0); } while (0)
; #define PG8_LDA(dst, b, h) do { _Pragma("unroll") for (int m = 0; m < 4; ++m) _Pragma("unroll") for (int k = 0; k < 2; ++k) dst[m][k] = *(const PG8_LAS bf16x8*)(lds + PG8_SA(b, h) + aoff + m * 2048 + k * 1024); } while (0)
; #define PG8_LDB(dst, b, h) do { _Pragma("unroll") for (int n = 0; n < 2; ++n) _Pragma("unroll") for (int k = 0; k < 2; ++k) dst[n][k] = *(const PG8_LAS bf16x8*)(lds + PG8_SB(b, h) + boff + n * 2048 + k * 1024); } while (0)
; #define PG8_MMA(ai, bj, At, Bt) do { __builtin_amdgcn_s_setprio(1); _Pragma("unroll") for (int m = 0; m < 4; ++m) _Pragma("unroll") for (int n = 0; n < 2; ++n) _Pragma("unroll") for (int k = 0; k < 2; ++k) \
;         acc[ai][bj][m][n] = __builtin_amdgcn_mfma_f32_16x16x32_bf16(Bt[n][k], At[m][k], acc[ai][bj][m][n], 0, 0, 0); __builtin_amdgcn_s_setprio(0); } while (0)
; #define PG8_WAIT_V(n) asm volatile("s_waitcnt vmcnt(" #n ")" ::: "memory")
; #define PG8_WAIT_L(n) asm volatile("s_waitcnt lgkmcnt(" #n ")" ::: "memory")
; template <class Epi, class Sched, bool ALIGN_EPI = false, bool SP2 = false>
; __device__ __forceinline__ void gemm_phase(PG8_LAS unsigned char* lds, const Gemm g, const Sched& S, const Epi& E, const int tid) {
;     ...
;             const bool last = (t == nt - 2);
;             const char* a1 = cA + (size_t)(t + 1) * kstep;
;             const char* a2 = last ? nA : cA + (size_t)(t + 2) * kstep; const char* b2 = last ? nB : cB + (size_t)(t + 2) * kstep;
;             const char* a3 = a2 + kstep; const char* b3 = b2 + kstep;
;             if (last && has_next) S.a_ready(nxt);
;             if constexpr (SP2) {
;             PG8_LDB(B0, 0, 0); PG8_LDB(B1, 0, 1); PG8_SCHED; PG8_LDA(At, 0, 0); PG8_STAGE(PG8_SA(1, 1), a1 + hstepA, voffA);
;             PG8_WAIT_V(8); PG8_WAIT_L(0); PG8_BAR; PG8_MMA(0, 0, At, B0); PG8_MMA(0, 1, At, B1); PG8_BAR; PG8_SCHED;
;             PG8_LDA(At, 0, 1); PG8_STAGE(PG8_SB(0, 0), b2, voffB); PG8_STAGE(PG8_SB(0, 1), b2 + hstepB, voffB); PG8_STAGE(PG8_SA(0, 0), a2, voffA);
;             PG8_WAIT_V(8); PG8_WAIT_L(0); PG8_BAR; PG8_MMA(1, 0, At, B0); PG8_MMA(1, 1, At, B1); PG8_BAR; PG8_SCHED;
.LBB0_175:
	s_add_u32 s22, s6, 0xfff80080
	s_addc_u32 s23, s7, -1
	s_add_i32 s60, 0, 0x10000
	s_cmp_eq_u32 s59, 28
	s_cselect_b32 s25, s17, s23
	s_cselect_b32 s24, s27, s22
	s_cselect_b32 s23, s15, s43
	s_cselect_b32 s22, s28, s29
	s_add_i32 s62, 0, 0x14000
	v_add_u32_e32 v140, s60, v225
	v_add_u32_e32 v156, s62, v225
	ds_read_b128 v[128:131], v140
	ds_read_b128 v[132:135], v140 offset:1024
	ds_read_b128 v[136:139], v140 offset:2048
	ds_read_b128 v[140:143], v140 offset:3072
	ds_read_b128 v[144:147], v156
	ds_read_b128 v[148:151], v156 offset:1024
	ds_read_b128 v[152:155], v156 offset:2048
	ds_read_b128 v[156:159], v156 offset:3072
	v_lshl_add_u64 v[202:203], s[6:7], 0, v[186:187]
	s_add_i32 m0, s46, 0xc000
	ds_read_b128 v[160:163], v226
	ds_read_b128 v[164:167], v226 offset:1024
	ds_read_b128 v[168:171], v226 offset:2048
	ds_read_b128 v[172:175], v226 offset:3072
	ds_read_b128 v[188:191], v226 offset:4096
	ds_read_b128 v[194:197], v226 offset:5120
	ds_read_b128 v[198:201], v226 offset:6144
	ds_read_b128 v[218:221], v226 offset:7168
	global_load_lds_dwordx4 v[202:203], off
	v_lshl_add_u64 v[202:203], s[6:7], 0, v[184:185]
	s_add_i32 m0, s46, 0xe000
	s_nop 0
	global_load_lds_dwordx4 v[202:203], off
	s_waitcnt vmcnt(8)
	s_waitcnt lgkmcnt(0)
	s_barrier
	s_setprio 1
	s_waitcnt lgkmcnt(0)
	v_mfma_f32_16x16x32_bf16 v[120:123], v[128:131], v[160:163], v[120:123]
	v_mfma_f32_16x16x32_bf16 v[76:79], v[128:131], v[168:171], v[76:79]
	v_mfma_f32_16x16x32_bf16 v[52:55], v[128:131], v[188:191], v[52:55]
	v_mfma_f32_16x16x32_bf16 v[32:35], v[128:131], v[198:201], v[32:35]
	v_mfma_f32_16x16x32_bf16 v[112:115], v[136:139], v[160:163], v[112:115]
	v_mfma_f32_16x16x32_bf16 v[60:63], v[136:139], v[168:171], v[60:63]
	v_mfma_f32_16x16x32_bf16 v[36:39], v[136:139], v[188:191], v[36:39]
	v_mfma_f32_16x16x32_bf16 v[24:27], v[136:139], v[198:201], v[24:27]
	v_mfma_f32_16x16x32_bf16 v[120:123], v[132:135], v[164:167], v[120:123]
	v_mfma_f32_16x16x32_bf16 v[76:79], v[132:135], v[172:175], v[76:79]
	v_mfma_f32_16x16x32_bf16 v[52:55], v[132:135], v[194:197], v[52:55]
	v_mfma_f32_16x16x32_bf16 v[32:35], v[132:135], v[218:221], v[32:35]
	v_mfma_f32_16x16x32_bf16 v[112:115], v[140:143], v[164:167], v[112:115]
	v_mfma_f32_16x16x32_bf16 v[60:63], v[140:143], v[172:175], v[60:63]
	v_mfma_f32_16x16x32_bf16 v[36:39], v[140:143], v[194:197], v[36:39]
	v_mfma_f32_16x16x32_bf16 v[24:27], v[140:143], v[218:221], v[24:27]
	s_setprio 0
	s_setprio 1
	v_mfma_f32_16x16x32_bf16 v[124:127], v[144:147], v[160:163], v[124:127]
	v_mfma_f32_16x16x32_bf16 v[84:87], v[144:147], v[168:171], v[84:87]
	v_mfma_f32_16x16x32_bf16 v[64:67], v[144:147], v[188:191], v[64:67]
	v_mfma_f32_16x16x32_bf16 v[44:47], v[144:147], v[198:201], v[44:47]
	v_mfma_f32_16x16x32_bf16 v[116:119], v[152:155], v[160:163], v[116:119]
	v_mfma_f32_16x16x32_bf16 v[68:71], v[152:155], v[168:171], v[68:71]
	v_mfma_f32_16x16x32_bf16 v[48:51], v[152:155], v[188:191], v[48:51]
	v_mfma_f32_16x16x32_bf16 v[28:31], v[152:155], v[198:201], v[28:31]
	v_mfma_f32_16x16x32_bf16 v[124:127], v[148:151], v[164:167], v[124:127]
	v_mfma_f32_16x16x32_bf16 v[84:87], v[148:151], v[172:175], v[84:87]
	v_mfma_f32_16x16x32_bf16 v[64:67], v[148:151], v[194:197], v[64:67]
	v_mfma_f32_16x16x32_bf16 v[44:47], v[148:151], v[218:221], v[44:47]
	v_mfma_f32_16x16x32_bf16 v[116:119], v[156:159], v[164:167], v[116:119]
	v_mfma_f32_16x16x32_bf16 v[68:71], v[156:159], v[172:175], v[68:71]
	v_mfma_f32_16x16x32_bf16 v[48:51], v[156:159], v[194:197], v[48:51]
	v_mfma_f32_16x16x32_bf16 v[28:31], v[156:159], v[218:221], v[28:31]
	s_setprio 0
	s_barrier
	s_add_i32 s60, s60, s37
	v_lshl_add_u64 v[202:203], s[22:23], 0, v[180:181]
	s_mov_b32 m0, s60
	ds_read_b128 v[160:163], v226 offset:16384
	ds_read_b128 v[164:167], v226 offset:17408
	ds_read_b128 v[168:171], v226 offset:18432
	ds_read_b128 v[172:175], v226 offset:19456
	ds_read_b128 v[188:191], v226 offset:20480
	ds_read_b128 v[194:197], v226 offset:21504
	ds_read_b128 v[198:201], v226 offset:22528
	ds_read_b128 v[218:221], v226 offset:23552
	global_load_lds_dwordx4 v[202:203], off
	s_add_i32 m0, s60, 0x2000
	s_add_u32 s60, s22, 0x80000
	v_lshl_add_u64 v[206:207], s[22:23], 0, v[176:177]
	s_addc_u32 s61, s23, 0
	s_add_i32 s62, s62, s37
	global_load_lds_dwordx4 v[206:207], off
	v_lshl_add_u64 v[208:209], s[60:61], 0, v[180:181]
	s_mov_b32 m0, s62
	v_lshl_add_u64 v[214:215], s[24:25], 0, v[178:179]
	global_load_lds_dwordx4 v[208:209], off
	v_lshl_add_u64 v[208:209], s[60:61], 0, v[176:177]
	s_add_i32 m0, s62, 0x2000
	s_nop 0
	global_load_lds_dwordx4 v[208:209], off
	v_lshl_add_u64 v[208:209], s[24:25], 0, v[182:183]
	s_mov_b32 m0, s46
	s_nop 0
	global_load_lds_dwordx4 v[208:209], off
	s_mov_b32 m0, s47
	s_nop 0
	global_load_lds_dwordx4 v[214:215], off
	s_waitcnt vmcnt(8)
	s_waitcnt lgkmcnt(0)
	s_barrier
; #define PG8_STAGE(bufoff, gbase, voff) do { _Pragma("unroll") for (int _i = 0; _i < 2; ++_i) \
;         __builtin_amdgcn_global_load_lds((const unsigned*)((const char*)(gbase) + (voff)[_i]), (PG8_LAS unsigned*)(lds + (bufoff) + ldsw + _i * 8192), 16, 0, 0); } while (0)
; #define PG8_LDA(dst, b, h) do { _Pragma("unroll") for (int m = 0; m < 4; ++m) _Pragma("unroll") for (int k = 0; k < 2; ++k) dst[m][k] = *(const PG8_LAS bf16x8*)(lds + PG8_SA(b, h) + aoff + m * 2048 + k * 1024); } while (0)
; #define PG8_LDB(dst, b, h) do { _Pragma("unroll") for (int n = 0; n < 2; ++n) _Pragma("unroll") for (int k = 0; k < 2; ++k) dst[n][k] = *(const PG8_LAS bf16x8*)(lds + PG8_SB(b, h) + boff + n * 2048 + k * 1024); } while (0)
; #define PG8_MMA(ai, bj, At, Bt) do { __builtin_amdgcn_s_setprio(1); _Pragma("unroll") for (int m = 0; m < 4; ++m) _Pragma("unroll") for (int n = 0; n < 2; ++n) _Pragma("unroll") for (int k = 0; k < 2; ++k) \
;         acc[ai][bj][m][n] = __builtin_amdgcn_mfma_f32_16x16x32_bf16(Bt[n][k], At[m][k], acc[ai][bj][m][n], 0, 0, 0); __builtin_amdgcn_s_setprio(0); } while (0)
; #define PG8_WAIT_V(n) asm volatile("s_waitcnt vmcnt(" #n ")" ::: "memory")
; #define PG8_WAIT_L(n) asm volatile("s_waitcnt lgkmcnt(" #n ")" ::: "memory")
; #define PG8_BAR __builtin_amdgcn_s_barrier()
; #define PG8_SCHED __builtin_amdgcn_sched_barrier(0)
; template <class Epi, class Sched, bool ALIGN_EPI = false, bool SP2 = false>
; __device__ __forceinline__ void gemm_phase(PG8_LAS unsigned char* lds, const Gemm g, const Sched& S, const Epi& E, const int tid) {
;     ...
;             PG8_WAIT_V(8); PG8_WAIT_L(0); PG8_BAR; PG8_MMA(1, 0, At, B0); PG8_MMA(1, 1, At, B1); PG8_BAR; PG8_SCHED;
;             PG8_LDB(B0, 1, 0); PG8_LDB(B1, 1, 1); PG8_SCHED; PG8_LDA(At, 1, 0); PG8_STAGE(PG8_SA(0, 1), a2 + hstepA, voffA);
;             PG8_WAIT_V(8); PG8_WAIT_L(0); PG8_BAR; PG8_MMA(0, 0, At, B0); PG8_MMA(0, 1, At, B1); PG8_BAR; PG8_SCHED;
	s_setprio 1
	s_waitcnt lgkmcnt(0)
	v_mfma_f32_16x16x32_bf16 v[96:99], v[128:131], v[160:163], v[96:99]
	v_mfma_f32_16x16x32_bf16 v[72:75], v[128:131], v[168:171], v[72:75]
	v_mfma_f32_16x16x32_bf16 v[16:19], v[128:131], v[188:191], v[16:19]
	v_mfma_f32_16x16x32_bf16 v[0:3], v[128:131], v[198:201], v[0:3]
	v_mfma_f32_16x16x32_bf16 v[100:103], v[136:139], v[160:163], v[100:103]
	v_mfma_f32_16x16x32_bf16 v[80:83], v[136:139], v[168:171], v[80:83]
	v_mfma_f32_16x16x32_bf16 v[20:23], v[136:139], v[188:191], v[20:23]
	v_mfma_f32_16x16x32_bf16 v[4:7], v[136:139], v[198:201], v[4:7]
	v_mfma_f32_16x16x32_bf16 v[96:99], v[132:135], v[164:167], v[96:99]
	v_mfma_f32_16x16x32_bf16 v[72:75], v[132:135], v[172:175], v[72:75]
	v_mfma_f32_16x16x32_bf16 v[16:19], v[132:135], v[194:197], v[16:19]
	v_mfma_f32_16x16x32_bf16 v[0:3], v[132:135], v[218:221], v[0:3]
	v_mfma_f32_16x16x32_bf16 v[100:103], v[140:143], v[164:167], v[100:103]
	v_mfma_f32_16x16x32_bf16 v[80:83], v[140:143], v[172:175], v[80:83]
	v_mfma_f32_16x16x32_bf16 v[20:23], v[140:143], v[194:197], v[20:23]
	v_mfma_f32_16x16x32_bf16 v[4:7], v[140:143], v[218:221], v[4:7]
	s_setprio 0
	s_setprio 1
	v_mfma_f32_16x16x32_bf16 v[108:111], v[144:147], v[160:163], v[108:111]
	v_mfma_f32_16x16x32_bf16 v[92:95], v[144:147], v[168:171], v[92:95]
	v_mfma_f32_16x16x32_bf16 v[56:59], v[144:147], v[188:191], v[56:59]
	v_mfma_f32_16x16x32_bf16 v[8:11], v[144:147], v[198:201], v[8:11]
	v_mfma_f32_16x16x32_bf16 v[104:107], v[152:155], v[160:163], v[104:107]
	v_mfma_f32_16x16x32_bf16 v[88:91], v[152:155], v[168:171], v[88:91]
	v_mfma_f32_16x16x32_bf16 v[40:43], v[152:155], v[188:191], v[40:43]
	v_mfma_f32_16x16x32_bf16 v[12:15], v[152:155], v[198:201], v[12:15]
	v_mfma_f32_16x16x32_bf16 v[108:111], v[148:151], v[164:167], v[108:111]
	v_mfma_f32_16x16x32_bf16 v[92:95], v[148:151], v[172:175], v[92:95]
	v_mfma_f32_16x16x32_bf16 v[56:59], v[148:151], v[194:197], v[56:59]
	v_mfma_f32_16x16x32_bf16 v[8:11], v[148:151], v[218:221], v[8:11]
	v_mfma_f32_16x16x32_bf16 v[104:107], v[156:159], v[164:167], v[104:107]
	v_mfma_f32_16x16x32_bf16 v[88:91], v[156:159], v[172:175], v[88:91]
	v_mfma_f32_16x16x32_bf16 v[40:43], v[156:159], v[194:197], v[40:43]
	v_mfma_f32_16x16x32_bf16 v[12:15], v[156:159], v[218:221], v[12:15]
	s_setprio 0
	s_barrier
	s_add_i32 s60, 0, 0x18000
	s_add_i32 s61, 0, 0x1c000
	v_add_u32_e32 v140, s60, v225
	v_add_u32_e32 v156, s61, v225
	ds_read_b128 v[128:131], v140
	ds_read_b128 v[132:135], v140 offset:1024
	ds_read_b128 v[136:139], v140 offset:2048
	ds_read_b128 v[140:143], v140 offset:3072
	ds_read_b128 v[144:147], v156
	ds_read_b128 v[148:151], v156 offset:1024
	ds_read_b128 v[152:155], v156 offset:2048
	ds_read_b128 v[156:159], v156 offset:3072
	s_add_u32 s24, s24, 0x80000
	s_addc_u32 s25, s25, 0
	s_mov_b32 m0, s48
	v_lshl_add_u64 v[216:217], s[24:25], 0, v[182:183]
	ds_read_b128 v[160:163], v226 offset:32768
	ds_read_b128 v[164:167], v226 offset:33792
	ds_read_b128 v[168:171], v226 offset:34816
	ds_read_b128 v[172:175], v226 offset:35840
	ds_read_b128 v[188:191], v226 offset:36864
	ds_read_b128 v[194:197], v226 offset:37888
	ds_read_b128 v[198:201], v226 offset:38912
	ds_read_b128 v[218:221], v226 offset:39936
	global_load_lds_dwordx4 v[216:217], off
	v_lshl_add_u64 v[216:217], s[24:25], 0, v[178:179]
	s_mov_b32 m0, s49
	s_nop 0
	global_load_lds_dwordx4 v[216:217], off
	s_waitcnt vmcnt(8)
	s_waitcnt lgkmcnt(0)
	s_barrier
	s_setprio 1
	s_waitcnt lgkmcnt(0)
	v_mfma_f32_16x16x32_bf16 v[120:123], v[128:131], v[160:163], v[120:123]
	v_mfma_f32_16x16x32_bf16 v[76:79], v[128:131], v[168:171], v[76:79]
	v_mfma_f32_16x16x32_bf16 v[52:55], v[128:131], v[188:191], v[52:55]
	v_mfma_f32_16x16x32_bf16 v[32:35], v[128:131], v[198:201], v[32:35]
	v_mfma_f32_16x16x32_bf16 v[112:115], v[136:139], v[160:163], v[112:115]
	v_mfma_f32_16x16x32_bf16 v[60:63], v[136:139], v[168:171], v[60:63]
	v_mfma_f32_16x16x32_bf16 v[36:39], v[136:139], v[188:191], v[36:39]
	v_mfma_f32_16x16x32_bf16 v[24:27], v[136:139], v[198:201], v[24:27]
	v_mfma_f32_16x16x32_bf16 v[120:123], v[132:135], v[164:167], v[120:123]
	v_mfma_f32_16x16x32_bf16 v[76:79], v[132:135], v[172:175], v[76:79]
	v_mfma_f32_16x16x32_bf16 v[52:55], v[132:135], v[194:197], v[52:55]
	v_mfma_f32_16x16x32_bf16 v[32:35], v[132:135], v[218:221], v[32:35]
	v_mfma_f32_16x16x32_bf16 v[112:115], v[140:143], v[164:167], v[112:115]
	v_mfma_f32_16x16x32_bf16 v[60:63], v[140:143], v[172:175], v[60:63]
	v_mfma_f32_16x16x32_bf16 v[36:39], v[140:143], v[194:197], v[36:39]
	v_mfma_f32_16x16x32_bf16 v[24:27], v[140:143], v[218:221], v[24:27]
	s_setprio 0
	s_setprio 1
	v_mfma_f32_16x16x32_bf16 v[124:127], v[144:147], v[160:163], v[124:127]
	v_mfma_f32_16x16x32_bf16 v[84:87], v[144:147], v[168:171], v[84:87]
	v_mfma_f32_16x16x32_bf16 v[64:67], v[144:147], v[188:191], v[64:67]
	v_mfma_f32_16x16x32_bf16 v[44:47], v[144:147], v[198:201], v[44:47]
	v_mfma_f32_16x16x32_bf16 v[116:119], v[152:155], v[160:163], v[116:119]
	v_mfma_f32_16x16x32_bf16 v[68:71], v[152:155], v[168:171], v[68:71]
	v_mfma_f32_16x16x32_bf16 v[48:51], v[152:155], v[188:191], v[48:51]
	v_mfma_f32_16x16x32_bf16 v[28:31], v[152:155], v[198:201], v[28:31]
	v_mfma_f32_16x16x32_bf16 v[124:127], v[148:151], v[164:167], v[124:127]
	v_mfma_f32_16x16x32_bf16 v[84:87], v[148:151], v[172:175], v[84:87]
	v_mfma_f32_16x16x32_bf16 v[64:67], v[148:151], v[194:197], v[64:67]
	v_mfma_f32_16x16x32_bf16 v[44:47], v[148:151], v[218:221], v[44:47]
	v_mfma_f32_16x16x32_bf16 v[116:119], v[156:159], v[164:167], v[116:119]
	v_mfma_f32_16x16x32_bf16 v[68:71], v[156:159], v[172:175], v[68:71]
	v_mfma_f32_16x16x32_bf16 v[48:51], v[156:159], v[194:197], v[48:51]
	v_mfma_f32_16x16x32_bf16 v[28:31], v[156:159], v[218:221], v[28:31]
	s_setprio 0
	s_barrier
; #define PG8_STAGE(bufoff, gbase, voff) do { _Pragma("unroll") for (int _i = 0; _i < 2; ++_i) \
;         __builtin_amdgcn_global_load_lds((const unsigned*)((const char*)(gbase) + (voff)[_i]), (PG8_LAS unsigned*)(lds + (bufoff) + ldsw + _i * 8192), 16, 0, 0); } while (0)
; #define PG8_LDA(dst, b, h) do { _Pragma("unroll") for (int m = 0; m < 4; ++m) _Pragma("unroll") for (int k = 0; k < 2; ++k) dst[m][k] = *(const PG8_LAS bf16x8*)(lds + PG8_SA(b, h) + aoff + m * 2048 + k * 1024); } while (0)
; #define PG8_MMA(ai, bj, At, Bt) do { __builtin_amdgcn_s_setprio(1); _Pragma("unroll") for (int m = 0; m < 4; ++m) _Pragma("unroll") for (int n = 0; n < 2; ++n) _Pragma("unroll") for (int k = 0; k < 2; ++k) \
;         acc[ai][bj][m][n] = __builtin_amdgcn_mfma_f32_16x16x32_bf16(Bt[n][k], At[m][k], acc[ai][bj][m][n], 0, 0, 0); __builtin_amdgcn_s_setprio(0); } while (0)
; #define PG8_WAIT_V(n) asm volatile("s_waitcnt vmcnt(" #n ")" ::: "memory")
; #define PG8_WAIT_L(n) asm volatile("s_waitcnt lgkmcnt(" #n ")" ::: "memory")
; #define PG8_BAR __builtin_amdgcn_s_barrier()
; #define PG8_SCHED __builtin_amdgcn_sched_barrier(0)
; template <class Epi, class Sched, bool ALIGN_EPI = false, bool SP2 = false>
; __device__ __forceinline__ void gemm_phase(PG8_LAS unsigned char* lds, const Gemm g, const Sched& S, const Epi& E, const int tid) {
;     ...
;             PG8_LDA(At, 1, 1); PG8_STAGE(PG8_SB(1, 0), b3, voffB); PG8_STAGE(PG8_SB(1, 1), b3 + hstepB, voffB); PG8_STAGE(PG8_SA(1, 0), a3, voffA);
;             PG8_WAIT_V(8); PG8_WAIT_L(0); PG8_BAR; PG8_MMA(1, 0, At, B0); PG8_MMA(1, 1, At, B1); PG8_BAR; PG8_SCHED;
	s_add_i32 s24, s60, s37
	v_lshl_add_u64 v[202:203], v[202:203], 0, s[82:83]
	s_mov_b32 m0, s24
	ds_read_b128 v[160:163], v226 offset:49152
	ds_read_b128 v[164:167], v226 offset:50176
	ds_read_b128 v[168:171], v226 offset:51200
	ds_read_b128 v[172:175], v226 offset:52224
	ds_read_b128 v[188:191], v226 offset:53248
	ds_read_b128 v[194:197], v226 offset:54272
	ds_read_b128 v[198:201], v226 offset:55296
	ds_read_b128 v[218:221], v226 offset:56320
	global_load_lds_dwordx4 v[202:203], off
	s_add_i32 m0, s24, 0x2000
	s_add_u32 s22, s22, 0x80080
	v_lshl_add_u64 v[202:203], v[206:207], 0, s[82:83]
	s_addc_u32 s23, s23, 0
	s_add_i32 s24, s61, s37
	global_load_lds_dwordx4 v[202:203], off
	v_lshl_add_u64 v[202:203], s[22:23], 0, v[180:181]
	s_mov_b32 m0, s24
	s_nop 0
	global_load_lds_dwordx4 v[202:203], off
	v_lshl_add_u64 v[202:203], s[22:23], 0, v[176:177]
	s_add_i32 m0, s24, 0x2000
	s_nop 0
	global_load_lds_dwordx4 v[202:203], off
	v_lshl_add_u64 v[202:203], v[208:209], 0, s[82:83]
	s_mov_b32 m0, s54
	s_nop 0
	global_load_lds_dwordx4 v[202:203], off
	v_lshl_add_u64 v[202:203], v[214:215], 0, s[82:83]
	s_mov_b32 m0, s55
	s_nop 0
	global_load_lds_dwordx4 v[202:203], off
	s_waitcnt vmcnt(8)
	s_waitcnt lgkmcnt(0)
	s_barrier
	s_setprio 1
	s_waitcnt lgkmcnt(0)
	v_mfma_f32_16x16x32_bf16 v[96:99], v[128:131], v[160:163], v[96:99]
	v_mfma_f32_16x16x32_bf16 v[72:75], v[128:131], v[168:171], v[72:75]
	v_mfma_f32_16x16x32_bf16 v[16:19], v[128:131], v[188:191], v[16:19]
	v_mfma_f32_16x16x32_bf16 v[0:3], v[128:131], v[198:201], v[0:3]
	v_mfma_f32_16x16x32_bf16 v[100:103], v[136:139], v[160:163], v[100:103]
	v_mfma_f32_16x16x32_bf16 v[80:83], v[136:139], v[168:171], v[80:83]
	v_mfma_f32_16x16x32_bf16 v[20:23], v[136:139], v[188:191], v[20:23]
	v_mfma_f32_16x16x32_bf16 v[4:7], v[136:139], v[198:201], v[4:7]
	v_mfma_f32_16x16x32_bf16 v[96:99], v[132:135], v[164:167], v[96:99]
	v_mfma_f32_16x16x32_bf16 v[72:75], v[132:135], v[172:175], v[72:75]
	v_mfma_f32_16x16x32_bf16 v[16:19], v[132:135], v[194:197], v[16:19]
	v_mfma_f32_16x16x32_bf16 v[0:3], v[132:135], v[218:221], v[0:3]
	v_mfma_f32_16x16x32_bf16 v[100:103], v[140:143], v[164:167], v[100:103]
	v_mfma_f32_16x16x32_bf16 v[80:83], v[140:143], v[172:175], v[80:83]
	v_mfma_f32_16x16x32_bf16 v[20:23], v[140:143], v[194:197], v[20:23]
	v_mfma_f32_16x16x32_bf16 v[4:7], v[140:143], v[218:221], v[4:7]
	s_setprio 0
	s_setprio 1
	v_mfma_f32_16x16x32_bf16 v[108:111], v[144:147], v[160:163], v[108:111]
	v_mfma_f32_16x16x32_bf16 v[92:95], v[144:147], v[168:171], v[92:95]
	v_mfma_f32_16x16x32_bf16 v[56:59], v[144:147], v[188:191], v[56:59]
	v_mfma_f32_16x16x32_bf16 v[8:11], v[144:147], v[198:201], v[8:11]
	v_mfma_f32_16x16x32_bf16 v[104:107], v[152:155], v[160:163], v[104:107]
	v_mfma_f32_16x16x32_bf16 v[88:91], v[152:155], v[168:171], v[88:91]
	v_mfma_f32_16x16x32_bf16 v[40:43], v[152:155], v[188:191], v[40:43]
	v_mfma_f32_16x16x32_bf16 v[12:15], v[152:155], v[198:201], v[12:15]
	v_mfma_f32_16x16x32_bf16 v[108:111], v[148:151], v[164:167], v[108:111]
	v_mfma_f32_16x16x32_bf16 v[92:95], v[148:151], v[172:175], v[92:95]
	v_mfma_f32_16x16x32_bf16 v[56:59], v[148:151], v[194:197], v[56:59]
	v_mfma_f32_16x16x32_bf16 v[8:11], v[148:151], v[218:221], v[8:11]
	v_mfma_f32_16x16x32_bf16 v[104:107], v[156:159], v[164:167], v[104:107]
	v_mfma_f32_16x16x32_bf16 v[88:91], v[156:159], v[172:175], v[88:91]
	v_mfma_f32_16x16x32_bf16 v[40:43], v[156:159], v[194:197], v[40:43]
	v_mfma_f32_16x16x32_bf16 v[12:15], v[156:159], v[218:221], v[12:15]
	s_setprio 0
	s_barrier
	s_add_i32 s59, s59, 2
	s_add_u32 s29, s29, 0x100
	s_addc_u32 s43, s43, 0
	s_add_u32 s6, s6, 0x100
	s_addc_u32 s7, s7, 0
	s_cmp_gt_u32 s59, 29
	s_cbranch_scc0 .LBB0_175
	s_and_b64 vcc, exec, s[12:13]
	s_cbranch_vccz .LBB0_178
	s_barrier
